# v36 + nt on the in-proj zcq/zckv f32 intermediate stores (read once by the small-ops phase)
# baseline (speedup 1.0000x reference)
; __device__ __forceinline__ void st_f32_sw(float* row, const f32x16& a, int hh) {
; #pragma unroll
;   for (int g = 0; g < 4; ++g) { f32x4 w = {a[4 * g], a[4 * g + 1], a[4 * g + 2], a[4 * g + 3]}; *(f32x4*)(row + 8 * g + 4 * hh) = w; }
; }
; __device__ void phase_inproj(const Params& p, char* lds) {
;     ...
;         } else if (nt < 26) {
;           st_f32_sw((float*)(ws + F_ZCQ) + (size_t)tok * 256 + (cb - 3072), acc[i][j], hh);
.Lp1_zcq:
	v_and_b32_e32 v165, 63, v181
	v_lshrrev_b32_e32 v167, 4, v165
	v_and_b32_e32 v168, 15, v165
	v_mul_u32_u24_e32 v166, 0x2200, v164
	v_mul_u32_u24_e32 v165, 0x110, v167
	v_add_u32_e32 v166, v166, v165
	v_add_u32_e32 v166, 0x8000, v166
	v_lshl_add_u32 v166, v168, 4, v166
	s_lshl_b32 s0, s53, 10
	s_sub_i32 s1, s54, 0xc00
	s_lshl_b32 s1, s1, 2
	s_add_i32 s0, s0, s1
	s_add_i32 s0, s0, 0x1699e000
	v_lshrrev_b32_e32 v170, 1, v164
	v_mul_u32_u24_e32 v170, 0x10000, v170
	v_mul_u32_u24_e32 v171, 0x400, v167
	v_add_u32_e32 v170, v170, v171
	v_and_b32_e32 v171, 1, v164
	v_mul_u32_u24_e32 v171, 0x100, v171
	v_lshl_add_u32 v171, v168, 4, v171
	v_add3_u32 v170, v170, v171, s0
	ds_write_b128 v138, v[48:51] offset:0
	ds_write_b128 v138, v[52:55] offset:32
	ds_write_b128 v138, v[56:59] offset:64
	ds_write_b128 v138, v[60:63] offset:96
	ds_write_b128 v138, v[32:35] offset:128
	ds_write_b128 v138, v[36:39] offset:160
	ds_write_b128 v138, v[40:43] offset:192
	ds_write_b128 v138, v[44:47] offset:224
	s_waitcnt lgkmcnt(0)
	ds_read_b128 v[32:35], v166 offset:0
	ds_read_b128 v[36:39], v166 offset:1088
	ds_read_b128 v[40:43], v166 offset:2176
	ds_read_b128 v[44:47], v166 offset:3264
	ds_read_b128 v[48:51], v166 offset:4352
	ds_read_b128 v[52:55], v166 offset:5440
	ds_read_b128 v[56:59], v166 offset:6528
	ds_read_b128 v[60:63], v166 offset:7616
	s_waitcnt lgkmcnt(7)
	global_store_dwordx4 v170, v[32:35], s[96:97] nt
	v_add_u32_e32 v170, 0x1000, v170
	s_waitcnt lgkmcnt(6)
	global_store_dwordx4 v170, v[36:39], s[96:97] nt
	v_add_u32_e32 v170, 0x1000, v170
	s_waitcnt lgkmcnt(5)
	global_store_dwordx4 v170, v[40:43], s[96:97] nt
	v_add_u32_e32 v170, 0x1000, v170
	s_waitcnt lgkmcnt(4)
	global_store_dwordx4 v170, v[44:47], s[96:97] nt
	v_add_u32_e32 v170, 0x1000, v170
	s_waitcnt lgkmcnt(3)
	global_store_dwordx4 v170, v[48:51], s[96:97] nt
	v_add_u32_e32 v170, 0x1000, v170
	s_waitcnt lgkmcnt(2)
	global_store_dwordx4 v170, v[52:55], s[96:97] nt
	v_add_u32_e32 v170, 0x1000, v170
	s_waitcnt lgkmcnt(1)
	global_store_dwordx4 v170, v[56:59], s[96:97] nt
	v_add_u32_e32 v170, 0x1000, v170
	s_waitcnt lgkmcnt(0)
	global_store_dwordx4 v170, v[60:63], s[96:97] nt
	v_add_u32_e32 v170, 0x1000, v170
	ds_write_b128 v138, v[16:19] offset:0
	ds_write_b128 v138, v[20:23] offset:32
	ds_write_b128 v138, v[24:27] offset:64
	ds_write_b128 v138, v[28:31] offset:96
	ds_write_b128 v138, v[0:3] offset:128
	ds_write_b128 v138, v[4:7] offset:160
	ds_write_b128 v138, v[8:11] offset:192
	ds_write_b128 v138, v[12:15] offset:224
	s_waitcnt lgkmcnt(0)
	ds_read_b128 v[0:3], v166 offset:0
	ds_read_b128 v[4:7], v166 offset:1088
	ds_read_b128 v[8:11], v166 offset:2176
	ds_read_b128 v[12:15], v166 offset:3264
	ds_read_b128 v[16:19], v166 offset:4352
	ds_read_b128 v[20:23], v166 offset:5440
	ds_read_b128 v[24:27], v166 offset:6528
	ds_read_b128 v[28:31], v166 offset:7616
	s_waitcnt lgkmcnt(7)
	global_store_dwordx4 v170, v[0:3], s[96:97] nt
	v_add_u32_e32 v170, 0x1000, v170
	s_waitcnt lgkmcnt(6)
	global_store_dwordx4 v170, v[4:7], s[96:97] nt
	v_add_u32_e32 v170, 0x1000, v170
	s_waitcnt lgkmcnt(5)
	global_store_dwordx4 v170, v[8:11], s[96:97] nt
	v_add_u32_e32 v170, 0x1000, v170
	s_waitcnt lgkmcnt(4)
	global_store_dwordx4 v170, v[12:15], s[96:97] nt
	v_add_u32_e32 v170, 0x1000, v170
	s_waitcnt lgkmcnt(3)
	global_store_dwordx4 v170, v[16:19], s[96:97] nt
	v_add_u32_e32 v170, 0x1000, v170
	s_waitcnt lgkmcnt(2)
	global_store_dwordx4 v170, v[20:23], s[96:97] nt
	v_add_u32_e32 v170, 0x1000, v170
	s_waitcnt lgkmcnt(1)
	global_store_dwordx4 v170, v[24:27], s[96:97] nt
	v_add_u32_e32 v170, 0x1000, v170
	s_waitcnt lgkmcnt(0)
	global_store_dwordx4 v170, v[28:31], s[96:97] nt
	v_add_u32_e32 v170, 0x1000, v170
	s_branch .LBB0_260
; __device__ __forceinline__ void st_f32_sw(float* row, const f32x16& a, int hh) {
; #pragma unroll
;   for (int g = 0; g < 4; ++g) { f32x4 w = {a[4 * g], a[4 * g + 1], a[4 * g + 2], a[4 * g + 3]}; *(f32x4*)(row + 8 * g + 4 * hh) = w; }
; }
; __device__ void phase_inproj(const Params& p, char* lds) {
;     ...
;         } else if (nt == 26) {
;           st_f32_sw((float*)(ws + F_ZCKV) + (size_t)tok * 128 + (cb - 3328), acc[i][j], hh);
.Lp1_zckv:
	v_and_b32_e32 v165, 63, v181
	v_lshrrev_b32_e32 v167, 4, v165
	v_and_b32_e32 v168, 15, v165
	v_mul_u32_u24_e32 v166, 0x2200, v164
	v_mul_u32_u24_e32 v165, 0x110, v167
	v_add_u32_e32 v166, v166, v165
	v_add_u32_e32 v166, 0x8000, v166
	v_lshl_add_u32 v166, v168, 4, v166
	s_lshl_b32 s0, s53, 9
	s_add_i32 s0, s0, 0x18a1e000
	v_lshrrev_b32_e32 v170, 1, v164
	v_mul_u32_u24_e32 v170, 0x8000, v170
	v_mul_u32_u24_e32 v171, 0x200, v167
	v_add_u32_e32 v170, v170, v171
	v_and_b32_e32 v171, 1, v164
	v_mul_u32_u24_e32 v171, 0x100, v171
	v_lshl_add_u32 v171, v168, 4, v171
	v_add3_u32 v170, v170, v171, s0
	ds_write_b128 v138, v[48:51] offset:0
	ds_write_b128 v138, v[52:55] offset:32
	ds_write_b128 v138, v[56:59] offset:64
	ds_write_b128 v138, v[60:63] offset:96
	ds_write_b128 v138, v[32:35] offset:128
	ds_write_b128 v138, v[36:39] offset:160
	ds_write_b128 v138, v[40:43] offset:192
	ds_write_b128 v138, v[44:47] offset:224
	s_waitcnt lgkmcnt(0)
	ds_read_b128 v[32:35], v166 offset:0
	ds_read_b128 v[36:39], v166 offset:1088
	ds_read_b128 v[40:43], v166 offset:2176
	ds_read_b128 v[44:47], v166 offset:3264
	ds_read_b128 v[48:51], v166 offset:4352
	ds_read_b128 v[52:55], v166 offset:5440
	ds_read_b128 v[56:59], v166 offset:6528
	ds_read_b128 v[60:63], v166 offset:7616
	s_waitcnt lgkmcnt(7)
	global_store_dwordx4 v170, v[32:35], s[96:97] nt
	v_add_u32_e32 v170, 0x800, v170
	s_waitcnt lgkmcnt(6)
	global_store_dwordx4 v170, v[36:39], s[96:97] nt
	v_add_u32_e32 v170, 0x800, v170
	s_waitcnt lgkmcnt(5)
	global_store_dwordx4 v170, v[40:43], s[96:97] nt
	v_add_u32_e32 v170, 0x800, v170
	s_waitcnt lgkmcnt(4)
	global_store_dwordx4 v170, v[44:47], s[96:97] nt
	v_add_u32_e32 v170, 0x800, v170
	s_waitcnt lgkmcnt(3)
	global_store_dwordx4 v170, v[48:51], s[96:97] nt
	v_add_u32_e32 v170, 0x800, v170
	s_waitcnt lgkmcnt(2)
	global_store_dwordx4 v170, v[52:55], s[96:97] nt
	v_add_u32_e32 v170, 0x800, v170
	s_waitcnt lgkmcnt(1)
	global_store_dwordx4 v170, v[56:59], s[96:97] nt
	v_add_u32_e32 v170, 0x800, v170
	s_waitcnt lgkmcnt(0)
	global_store_dwordx4 v170, v[60:63], s[96:97] nt
	v_add_u32_e32 v170, 0x800, v170
	ds_write_b128 v138, v[16:19] offset:0
	ds_write_b128 v138, v[20:23] offset:32
	ds_write_b128 v138, v[24:27] offset:64
	ds_write_b128 v138, v[28:31] offset:96
	ds_write_b128 v138, v[0:3] offset:128
	ds_write_b128 v138, v[4:7] offset:160
	ds_write_b128 v138, v[8:11] offset:192
	ds_write_b128 v138, v[12:15] offset:224
	s_waitcnt lgkmcnt(0)
	ds_read_b128 v[0:3], v166 offset:0
	ds_read_b128 v[4:7], v166 offset:1088
	ds_read_b128 v[8:11], v166 offset:2176
	ds_read_b128 v[12:15], v166 offset:3264
	ds_read_b128 v[16:19], v166 offset:4352
	ds_read_b128 v[20:23], v166 offset:5440
	ds_read_b128 v[24:27], v166 offset:6528
	ds_read_b128 v[28:31], v166 offset:7616
	s_waitcnt lgkmcnt(7)
	global_store_dwordx4 v170, v[0:3], s[96:97] nt
	v_add_u32_e32 v170, 0x800, v170
	s_waitcnt lgkmcnt(6)
	global_store_dwordx4 v170, v[4:7], s[96:97] nt
	v_add_u32_e32 v170, 0x800, v170
	s_waitcnt lgkmcnt(5)
	global_store_dwordx4 v170, v[8:11], s[96:97] nt
	v_add_u32_e32 v170, 0x800, v170
	s_waitcnt lgkmcnt(4)
	global_store_dwordx4 v170, v[12:15], s[96:97] nt
	v_add_u32_e32 v170, 0x800, v170
	s_waitcnt lgkmcnt(3)
	global_store_dwordx4 v170, v[16:19], s[96:97] nt
	v_add_u32_e32 v170, 0x800, v170
	s_waitcnt lgkmcnt(2)
	global_store_dwordx4 v170, v[20:23], s[96:97] nt
	v_add_u32_e32 v170, 0x800, v170
	s_waitcnt lgkmcnt(1)
	global_store_dwordx4 v170, v[24:27], s[96:97] nt
	v_add_u32_e32 v170, 0x800, v170
	s_waitcnt lgkmcnt(0)
	global_store_dwordx4 v170, v[28:31], s[96:97] nt
	v_add_u32_e32 v170, 0x800, v170
	s_branch .LBB0_260
